# rg_prompt_item head: history-row loads and the first 26 z loads issued before the single wait for the gate-weight loads (three serialized round trips become one)
# speedup vs baseline: 1.0118x; 1.0118x over previous
; #define LAS __attribute__((address_space(3)))
; __device__ __forceinline__ float bf2f(unsigned b) { return __uint_as_float(b << 16); }
; __device__ __forceinline__ float softplus_(float x) { return fmaxf(x, 0.f) + __logf(1.f + __expf(-fabsf(x))); }
; __device__ __forceinline__ void rg_load_const(const Ctx& P, int l, int ch, int nb, int lane, RgConst& c, bf16x8 (&bw)[2][4][2]) {
;     const float* p_cw = INP(P, 9);
;     c.cw0 = p_cw[(size_t)(l * 4 + 0) * D + ch]; c.cw1 = p_cw[(size_t)(l * 4 + 1) * D + ch]; c.cw2 = p_cw[(size_t)(l * 4 + 2) * D + ch]; c.cw3 = p_cw[(size_t)(l * 4 + 3) * D + ch];
;     c.cb = INP(P, 10)[l * D + ch]; c.ba = INP(P, 12)[l * D + ch]; c.bx = INP(P, 14)[l * D + ch]; c.sp8 = 8.f * softplus_(-INP(P, 15)[l * D + ch]);
;     const bf16_t* RGW = (const bf16_t*)(P.ws + WS_RGW);
;     const int fr = lane & 15, fq = lane >> 4;
; #pragma unroll
;     for (int g = 0; g < 2; ++g)
; #pragma unroll
;         for (int ct = 0; ct < 4; ++ct)
; #pragma unroll
;             for (int ks = 0; ks < 2; ++ks) bw[g][ct][ks] = *(const bf16x8*)(RGW + ((((size_t)l * 2 + g) * 16 + nb) * 64 + 16 * ct + fr) * 64 + ks * 32 + fq * 8);
; }
; __device__ __forceinline__ void rg_prompt_item(const Ctx& P, int l, int wi, LAS unsigned char* wl, int lane) {
;     const int nb = wi & 15, c = wi < 4096 ? 1 + ((wi >> 4) & 31) : 0, b = wi < 4096 ? wi >> 9 : (wi - 4096) >> 4;
;     const int L = c == 0 ? 16 : 64, t0 = c == 0 ? 0 : 16 + 64 * (c - 1), row0 = b * TP + t0, ch = nb * 64 + lane;
;     const bf16_t* Z = (const bf16_t*)(P.ws + WS_Z); bf16_t* HG = (bf16_t*)(P.ws + WS_HG); bf16_t* A2 = (bf16_t*)(P.ws + WS_T); float* CAR = (float*)(P.ws + WS_CARRY);
;     RgConst k; bf16x8 bw[2][4][2]; rg_load_const(P, l, ch, nb, lane, k, bw);
;     float xm3 = 0.f, xm2 = 0.f, xm1 = 0.f;
;     if (t0 > 0) { xm3 = bf2f(Z[(size_t)(row0 - 3) * NZ + ch]); xm2 = bf2f(Z[(size_t)(row0 - 2) * NZ + ch]); xm1 = bf2f(Z[(size_t)(row0 - 1) * NZ + ch]); }
;     float h = 0.f, pacc = 1.f;
;     unsigned xr[16], yr[16];
; #pragma unroll
;     for (int i = 0; i < 16; ++i) { xr[i] = Z[(size_t)(row0 + i) * NZ + ch]; yr[i] = Z[(size_t)(row0 + i) * NZ + ZC_RGY + ch]; }
.LBB0_338:
	s_andn2_b64 vcc, exec, s[0:1]
	s_cbranch_vccnz .LBB0_210
	s_bfe_u32 s0, s45, 0x50004
	s_add_i32 s4, s0, 1
	s_cmpk_gt_i32 s45, 0xfff
	s_cselect_b64 s[0:1], -1, 0
	s_and_b64 s[0:1], s[0:1], exec
	s_cselect_b32 s4, 0, s4
	s_lshl_b32 s0, s4, 6
	s_sub_i32 s5, s0, 48
	s_cmpk_gt_i32 s45, 0xfff
	s_cselect_b64 s[0:1], -1, 0
	s_and_b64 s[0:1], s[0:1], exec
	s_cselect_b32 s23, 0, s5
	s_add_i32 s0, s45, 0xfffff000
	s_ashr_i32 s5, s45, 9
	s_lshr_b32 s22, s0, 4
	s_cmpk_gt_i32 s45, 0xfff
	s_cselect_b64 s[0:1], -1, 0
	s_and_b64 s[14:15], s[0:1], exec
	v_readlane_b32 s15, v250, 15
	s_cselect_b32 s5, s22, s5
	s_mul_i32 s14, s5, 0x810
	v_mov_b32_e32 v0, s15
	ds_read2_b64 v[2:5], v0 offset1:1
	s_add_i32 s22, s23, s14
	s_lshl_b32 s14, s45, 6
	s_and_b32 s30, s14, 0x3c0
	v_readlane_b32 s14, v250, 16
	v_or_b32_e32 v110, s30, v83
	s_waitcnt lgkmcnt(0)
	v_readfirstlane_b32 s15, v3
	v_mov_b32_e32 v0, s14
	v_readfirstlane_b32 s14, v2
	s_add_u32 s14, s14, s40
	ds_read_b64 v[6:7], v0
	s_addc_u32 s15, s15, 0
	v_lshlrev_b32_e32 v0, 2, v110
	v_lshl_add_u64 v[2:3], s[14:15], 0, v[0:1]
	s_movk_i32 s38, 0x1000
	v_add_co_u32_e32 v8, vcc, s38, v2
	v_readfirstlane_b32 s15, v5
	s_nop 0
	v_addc_co_u32_e32 v9, vcc, 0, v3, vcc
	v_add_co_u32_e32 v10, vcc, s7, v2
	v_readfirstlane_b32 s14, v4
	s_nop 0
	v_addc_co_u32_e32 v11, vcc, 0, v3, vcc
	v_add_co_u32_e32 v12, vcc, s2, v2
	s_cmp_lt_i32 s23, 1
	s_nop 0
	v_addc_co_u32_e32 v13, vcc, 0, v3, vcc
	flat_load_dword v87, v[2:3]
	flat_load_dword v111, v[8:9]
	flat_load_dword v112, v[10:11]
	flat_load_dword v113, v[12:13]
	v_or_b32_e32 v2, s41, v110
	v_mov_b32_e32 v3, v1
	v_lshlrev_b64 v[8:9], 2, v[2:3]
	v_lshl_add_u64 v[2:3], s[14:15], 0, v[8:9]
	v_readlane_b32 s14, v250, 17
	flat_load_dword v114, v[2:3]
	s_waitcnt lgkmcnt(0)
	v_readfirstlane_b32 s15, v7
	v_mov_b32_e32 v2, s14
	ds_read_b128 v[2:5], v2
	v_readfirstlane_b32 s14, v6
	s_mul_i32 s23, s22, 0x3a00
	v_lshlrev_b32_e32 v84, 1, v110
	v_lshl_add_u64 v[6:7], s[14:15], 0, v[8:9]
	s_waitcnt lgkmcnt(0)
	v_readfirstlane_b32 s15, v3
	v_readfirstlane_b32 s14, v2
	flat_load_dword v115, v[6:7]
	s_nop 0
	v_lshl_add_u64 v[2:3], s[14:15], 0, v[8:9]
	v_readfirstlane_b32 s15, v5
	v_readfirstlane_b32 s14, v4
	flat_load_dword v116, v[2:3]
	s_nop 0
	v_lshl_add_u64 v[2:3], s[14:15], 0, v[8:9]
	flat_load_dword v66, v[2:3]
	v_or_b32_e32 v2, s30, v82
	v_mov_b32_e32 v3, v79
	v_lshlrev_b64 v[2:3], 7, v[2:3]
	v_lshl_add_u64 v[50:51], v[80:81], 0, v[2:3]
	v_add_co_u32_e32 v30, vcc, s38, v50
	s_mov_b32 s14, 0x20000
	s_nop 0
	v_addc_co_u32_e32 v31, vcc, 0, v51, vcc
	v_add_co_u32_e32 v46, vcc, s14, v50
	global_load_dwordx4 v[2:5], v[50:51], off
	global_load_dwordx4 v[6:9], v[50:51], off offset:64
	global_load_dwordx4 v[10:13], v[50:51], off offset:2048
	global_load_dwordx4 v[14:17], v[50:51], off offset:2112
	v_addc_co_u32_e32 v47, vcc, 0, v51, vcc
	v_add_co_u32_e32 v62, vcc, 0x21000, v50
	global_load_dwordx4 v[18:21], v[30:31], off
	global_load_dwordx4 v[22:25], v[30:31], off offset:64
	global_load_dwordx4 v[26:29], v[30:31], off offset:2048
	s_nop 0
	global_load_dwordx4 v[30:33], v[30:31], off offset:2112
	v_addc_co_u32_e32 v63, vcc, 0, v51, vcc
	global_load_dwordx4 v[34:37], v[46:47], off
	global_load_dwordx4 v[38:41], v[46:47], off offset:64
	global_load_dwordx4 v[42:45], v[46:47], off offset:2048
	s_nop 0
	global_load_dwordx4 v[46:49], v[46:47], off offset:2112
	s_nop 0
	global_load_dwordx4 v[50:53], v[62:63], off
	global_load_dwordx4 v[54:57], v[62:63], off offset:64
	global_load_dwordx4 v[58:61], v[62:63], off offset:2048
	s_nop 0
	global_load_dwordx4 v[62:65], v[62:63], off offset:2112
	s_mov_b32 s14, 0
	s_cbranch_scc1 .LBB0_341
	s_add_i32 s15, s22, -3
	s_add_i32 s30, s23, 0xffff5200
	s_mul_hi_i32 s15, s15, 0x3a00
	s_add_u32 s38, s16, s30
	s_addc_u32 s39, s17, s15
	s_add_i32 s15, s22, -2
	s_add_i32 s30, s23, 0xffff8c00
	s_mul_hi_i32 s15, s15, 0x3a00
	s_add_u32 s46, s16, s30
	s_addc_u32 s47, s17, s15
	global_load_ushort v67, v84, s[38:39] nt
	global_load_ushort v68, v84, s[46:47] nt
	s_add_i32 s15, s22, -1
	s_add_i32 s30, s23, 0xffffc600
	s_mul_hi_i32 s15, s15, 0x3a00
	s_add_u32 s38, s16, s30
	s_addc_u32 s39, s17, s15
	global_load_ushort v69, v84, s[38:39] nt
	s_branch .LBB0_342
.LBB0_341:
	v_mov_b32_e32 v67, 0
	v_mov_b32_e32 v68, 0
	v_mov_b32_e32 v69, 0
	v_mov_b32_e32 v95, 0
; #define LAS __attribute__((address_space(3)))
; __device__ __forceinline__ float bf2f(unsigned b) { return __uint_as_float(b << 16); }
; __device__ __forceinline__ float softplus_(float x) { return fmaxf(x, 0.f) + __logf(1.f + __expf(-fabsf(x))); }
; __device__ __forceinline__ void rg_load_const(const Ctx& P, int l, int ch, int nb, int lane, RgConst& c, bf16x8 (&bw)[2][4][2]) {
;     ...
;     c.cb = INP(P, 10)[l * D + ch]; c.ba = INP(P, 12)[l * D + ch]; c.bx = INP(P, 14)[l * D + ch]; c.sp8 = 8.f * softplus_(-INP(P, 15)[l * D + ch]);
;     const bf16_t* RGW = (const bf16_t*)(P.ws + WS_RGW);
;     const int fr = lane & 15, fq = lane >> 4;
; #pragma unroll
;     for (int g = 0; g < 2; ++g)
; #pragma unroll
;         for (int ct = 0; ct < 4; ++ct)
; #pragma unroll
;             for (int ks = 0; ks < 2; ++ks) bw[g][ct][ks] = *(const bf16x8*)(RGW + ((((size_t)l * 2 + g) * 16 + nb) * 64 + 16 * ct + fr) * 64 + ks * 32 + fq * 8);
; }
; __device__ __forceinline__ void rg_prompt_item(const Ctx& P, int l, int wi, LAS unsigned char* wl, int lane) {
;     const int nb = wi & 15, c = wi < 4096 ? 1 + ((wi >> 4) & 31) : 0, b = wi < 4096 ? wi >> 9 : (wi - 4096) >> 4;
;     const int L = c == 0 ? 16 : 64, t0 = c == 0 ? 0 : 16 + 64 * (c - 1), row0 = b * TP + t0, ch = nb * 64 + lane;
;     const bf16_t* Z = (const bf16_t*)(P.ws + WS_Z); bf16_t* HG = (bf16_t*)(P.ws + WS_HG); bf16_t* A2 = (bf16_t*)(P.ws + WS_T); float* CAR = (float*)(P.ws + WS_CARRY);
;     RgConst k; bf16x8 bw[2][4][2]; rg_load_const(P, l, ch, nb, lane, k, bw);
;     float xm3 = 0.f, xm2 = 0.f, xm1 = 0.f;
;     if (t0 > 0) { xm3 = bf2f(Z[(size_t)(row0 - 3) * NZ + ch]); xm2 = bf2f(Z[(size_t)(row0 - 2) * NZ + ch]); xm1 = bf2f(Z[(size_t)(row0 - 1) * NZ + ch]); }
;     float h = 0.f, pacc = 1.f;
;     unsigned xr[16], yr[16];
; #pragma unroll
;     for (int i = 0; i < 16; ++i) { xr[i] = Z[(size_t)(row0 + i) * NZ + ch]; yr[i] = Z[(size_t)(row0 + i) * NZ + ZC_RGY + ch]; }
.LBB0_342:
	s_and_b64 s[0:1], s[0:1], exec
	s_cselect_b32 s15, 1, 4
	s_mul_hi_i32 s1, s22, 0x3a00
	s_add_u32 s0, s16, s23
	s_addc_u32 s1, s17, s1
	global_load_ushort v165, v84, s[0:1] nt
	global_load_ushort v89, v84, s[0:1] offset:2048 nt
	s_or_b32 s0, s22, 1
	s_mul_hi_i32 s1, s0, 0x3a00
	s_mulk_i32 s0, 0x3a00
	s_add_u32 s0, s16, s0
	s_addc_u32 s1, s17, s1
	global_load_ushort v168, v84, s[0:1] nt
	global_load_ushort v158, v84, s[0:1] offset:2048 nt
	s_or_b32 s0, s22, 2
	s_mul_hi_i32 s1, s0, 0x3a00
	s_mulk_i32 s0, 0x3a00
	s_add_u32 s0, s16, s0
	s_addc_u32 s1, s17, s1
	global_load_ushort v170, v84, s[0:1] nt
	global_load_ushort v159, v84, s[0:1] offset:2048 nt
	s_or_b32 s0, s22, 3
	s_mul_hi_i32 s1, s0, 0x3a00
	s_mulk_i32 s0, 0x3a00
	s_add_u32 s0, s16, s0
	s_addc_u32 s1, s17, s1
	global_load_ushort v174, v84, s[0:1] nt
	global_load_ushort v160, v84, s[0:1] offset:2048 nt
	s_or_b32 s0, s22, 4
	s_mul_hi_i32 s1, s0, 0x3a00
	s_mulk_i32 s0, 0x3a00
	s_add_u32 s0, s16, s0
	s_addc_u32 s1, s17, s1
	global_load_ushort v173, v84, s[0:1] nt
	global_load_ushort v161, v84, s[0:1] offset:2048 nt
	s_or_b32 s0, s22, 5
	s_mul_hi_i32 s1, s0, 0x3a00
	s_mulk_i32 s0, 0x3a00
	s_add_u32 s0, s16, s0
	s_addc_u32 s1, s17, s1
	global_load_ushort v172, v84, s[0:1] nt
	global_load_ushort v162, v84, s[0:1] offset:2048 nt
	s_or_b32 s0, s22, 6
	s_mul_hi_i32 s1, s0, 0x3a00
	s_mulk_i32 s0, 0x3a00
	s_add_u32 s0, s16, s0
	s_addc_u32 s1, s17, s1
	global_load_ushort v171, v84, s[0:1] nt
	global_load_ushort v163, v84, s[0:1] offset:2048 nt
	s_or_b32 s0, s22, 7
	s_mul_hi_i32 s1, s0, 0x3a00
	s_mulk_i32 s0, 0x3a00
	s_add_u32 s0, s16, s0
	s_addc_u32 s1, s17, s1
	global_load_ushort v169, v84, s[0:1] nt
	global_load_ushort v164, v84, s[0:1] offset:2048 nt
	s_or_b32 s0, s22, 8
	s_mul_hi_i32 s1, s0, 0x3a00
	s_mulk_i32 s0, 0x3a00
	s_add_u32 s0, s16, s0
	s_addc_u32 s1, s17, s1
	global_load_ushort v167, v84, s[0:1] nt
	global_load_ushort v166, v84, s[0:1] offset:2048 nt
	s_or_b32 s0, s22, 9
	s_mul_hi_i32 s1, s0, 0x3a00
	s_mulk_i32 s0, 0x3a00
	s_add_u32 s0, s16, s0
	s_addc_u32 s1, s17, s1
	global_load_ushort v103, v84, s[0:1] nt
	global_load_ushort v101, v84, s[0:1] offset:2048 nt
	s_or_b32 s0, s22, 10
	s_mul_hi_i32 s1, s0, 0x3a00
	s_mulk_i32 s0, 0x3a00
	s_add_u32 s0, s16, s0
	s_addc_u32 s1, s17, s1
	global_load_ushort v102, v84, s[0:1] nt
	global_load_ushort v100, v84, s[0:1] offset:2048 nt
	s_or_b32 s0, s22, 11
	s_mul_hi_i32 s1, s0, 0x3a00
	s_mulk_i32 s0, 0x3a00
	s_add_u32 s0, s16, s0
	s_addc_u32 s1, s17, s1
	global_load_ushort v99, v84, s[0:1] nt
	global_load_ushort v98, v84, s[0:1] offset:2048 nt
	s_or_b32 s0, s22, 12
	s_mul_hi_i32 s1, s0, 0x3a00
	s_mulk_i32 s0, 0x3a00
	s_add_u32 s0, s16, s0
	s_addc_u32 s1, s17, s1
	global_load_ushort v73, v84, s[0:1] nt
	global_load_ushort v72, v84, s[0:1] offset:2048 nt
	s_mov_b32 s0, 0xbfb8aa3b
	s_waitcnt vmcnt(26) lgkmcnt(0)
	v_lshlrev_b32_e32 v92, 16, v67
	v_lshlrev_b32_e32 v93, 16, v68
	v_lshlrev_b32_e32 v94, 16, v69
	v_max_f32_e64 v67, -v66, -v66
	v_mul_f32_e64 v66, |v66|, s0
	v_exp_f32_e32 v66, v66
	s_mov_b32 s0, 0x3f317217
	v_max_f32_e32 v67, 0, v67
	v_add_f32_e32 v66, 1.0, v66
	v_cmp_gt_f32_e32 vcc, s66, v66
	v_mov_b32_e32 v85, v1
	v_mov_b32_e32 v88, 0
	v_cndmask_b32_e64 v68, 0, 32, vcc
	v_ldexp_f32 v66, v66, v68
	v_log_f32_e32 v66, v66
	v_mov_b32_e32 v86, 1.0
	v_mul_f32_e32 v68, 0x3f317217, v66
	v_fma_f32 v68, v66, s0, -v68
	v_fmac_f32_e32 v68, 0x3377d1cf, v66
	s_mov_b32 s0, 0x7f800000
	v_fmac_f32_e32 v68, 0x3f317217, v66
	v_cmp_lt_f32_e64 s[0:1], |v66|, s0
	s_nop 1
	v_cndmask_b32_e64 v66, v66, v68, s[0:1]
	s_or_b32 s0, s22, 13
	s_mul_hi_i32 s1, s0, 0x3a00
	s_mulk_i32 s0, 0x3a00
	v_cndmask_b32_e32 v68, 0, v195, vcc
	s_add_u32 s0, s16, s0
	v_sub_f32_e32 v66, v66, v68
	s_addc_u32 s1, s17, s1
	v_add_f32_e32 v90, v67, v66
	global_load_ushort v66, v84, s[0:1] nt
	global_load_ushort v71, v84, s[0:1] offset:2048 nt
	s_or_b32 s0, s22, 14
	s_mul_hi_i32 s1, s0, 0x3a00
	s_mulk_i32 s0, 0x3a00
	s_add_u32 s0, s16, s0
	s_addc_u32 s1, s17, s1
	global_load_ushort v67, v84, s[0:1] nt
	global_load_ushort v70, v84, s[0:1] offset:2048 nt
	s_or_b32 s0, s22, 15
	s_mul_hi_i32 s1, s0, 0x3a00
	s_mulk_i32 s0, 0x3a00
	s_add_u32 s0, s16, s0
	s_addc_u32 s1, s17, s1
	global_load_ushort v69, v84, s[0:1] nt
	global_load_ushort v68, v84, s[0:1] offset:2048 nt
	v_mul_f32_e32 v95, 0xc1000000, v90
	v_lshl_add_u64 v[90:91], s[16:17], 0, v[84:85]
	s_add_i32 s22, s22, 31
	s_waitcnt vmcnt(30)
	v_mov_b32_e32 v85, v89
	s_waitcnt vmcnt(28)
	v_mov_b32_e32 v117, v158
	s_waitcnt vmcnt(26)
	v_mov_b32_e32 v119, v159
	s_waitcnt vmcnt(24)
	v_mov_b32_e32 v122, v160
	v_mov_b32_e32 v118, v165
	v_mov_b32_e32 v120, v168
	v_mov_b32_e32 v121, v170
	s_waitcnt vmcnt(22)
	v_mov_b32_e32 v123, v161
	v_mov_b32_e32 v124, v174
	v_mov_b32_e32 v126, v173
	s_waitcnt vmcnt(21)
	v_mov_b32_e32 v128, v172
	s_waitcnt vmcnt(20)
	v_mov_b32_e32 v125, v162
	s_waitcnt vmcnt(19)
	v_mov_b32_e32 v129, v171
	s_waitcnt vmcnt(18)
	v_mov_b32_e32 v127, v163
	s_waitcnt vmcnt(17)
	v_mov_b32_e32 v144, v169
	s_waitcnt vmcnt(16)
	v_mov_b32_e32 v142, v164
	s_waitcnt vmcnt(15)
	v_mov_b32_e32 v146, v167
	s_waitcnt vmcnt(14)
	v_mov_b32_e32 v143, v166
	s_waitcnt vmcnt(13)
	v_mov_b32_e32 v148, v103
	s_waitcnt vmcnt(12)
	v_mov_b32_e32 v145, v101
	s_waitcnt vmcnt(11)
	v_mov_b32_e32 v149, v102
	s_waitcnt vmcnt(10)
	v_mov_b32_e32 v147, v100
	s_waitcnt vmcnt(9)
	v_mov_b32_e32 v152, v99
	s_waitcnt vmcnt(8)
	v_mov_b32_e32 v150, v98
	s_waitcnt vmcnt(7)
	v_mov_b32_e32 v154, v73
	s_waitcnt vmcnt(6)
	v_mov_b32_e32 v151, v72
	s_waitcnt vmcnt(4)
	v_mov_b32_e32 v153, v71
	s_waitcnt vmcnt(3)
	v_mov_b64_e32 v[96:97], v[66:67]
	s_waitcnt vmcnt(2)
	v_mov_b32_e32 v155, v70
	s_waitcnt vmcnt(1)
	v_mov_b32_e32 v157, v69
	s_waitcnt vmcnt(0)
	v_mov_b32_e32 v156, v68
	s_add_i32 s14, s14, 1
	s_cmp_ge_u32 s14, s15
	s_cbranch_scc1 .LBB0_344
